# out-proj epilogue residual loads double-buffered (two batches in flight) instead of issue-wait per batch, on top of v26
# speedup vs baseline: 1.0043x; 1.0043x over previous
.LBB0_675:
	s_lshr_b32 s0, s94, 3
	s_mulk_i32 s0, 0x6000
	s_ashr_i32 s1, s0, 31
	s_lshl_b64 s[0:1], s[0:1], 2
	s_add_u32 s0, s87, s0
	s_addc_u32 s1, s64, s1
	s_lshl_b32 s18, s94, 8
	v_mov_b32_e32 v199, v183
	v_add_u32_e32 v146, s18, v1
	v_lshl_add_u64 v[130:131], s[0:1], 0, v[198:199]
	v_ashrrev_i32_e32 v147, 31, v146
	v_lshl_add_u64 v[142:143], v[130:131], 0, s[54:55]
	v_add_co_u32_e32 v130, vcc, s65, v130
	v_lshlrev_b64 v[134:135], 14, v[146:147]
	s_nop 0
	v_addc_co_u32_e32 v131, vcc, 0, v131, vcc
	v_lshl_add_u64 v[160:161], v[186:187], 0, v[134:135]
	global_load_dwordx4 v[130:133], v[130:131], off
	s_nop 0
	global_load_dwordx4 v[148:151], v[160:161], off
	global_load_dwordx4 v[152:155], v[160:161], off offset:64
	global_load_dwordx4 v[138:141], v[142:143], off offset:64
	global_load_dwordx4 v[134:137], v[142:143], off offset:512
	global_load_dwordx4 v[156:159], v[160:161], off offset:512
	s_nop 0
	global_load_dwordx4 v[142:145], v[142:143], off offset:576
	s_nop 0
	global_load_dwordx4 v[160:163], v[160:161], off offset:576
	v_add_u32_e32 v164, s18, v221
	v_ashrrev_i32_e32 v165, 31, v164
	v_lshlrev_b64 v[164:165], 14, v[164:165]
	v_lshl_add_u64 v[164:165], v[186:187], 0, v[164:165]
	v_readfirstlane_b32 s19, v0
	global_load_dwordx4 v[202:205], v[164:165], off
	global_load_dwordx4 v[206:209], v[164:165], off offset:64
	global_load_dwordx4 v[210:213], v[164:165], off offset:512
	global_load_dwordx4 v[214:217], v[164:165], off offset:576
	v_add_u32_e32 v164, s18, v223
	v_ashrrev_i32_e32 v165, 31, v164
	v_lshlrev_b64 v[164:165], 14, v[164:165]
	v_lshl_add_u64 v[164:165], v[186:187], 0, v[164:165]
	s_waitcnt vmcnt(4)
	v_pk_fma_f32 v[60:61], v[60:61], v[140:141], v[154:155]
	v_pk_fma_f32 v[58:59], v[58:59], v[138:139], v[152:153]
	v_pk_fma_f32 v[28:29], v[28:29], v[136:137], v[158:159]
	v_pk_fma_f32 v[92:93], v[92:93], v[132:133], v[150:151]
	v_pk_fma_f32 v[90:91], v[90:91], v[130:131], v[148:149]
	v_pk_fma_f32 v[26:27], v[26:27], v[134:135], v[156:157]
	v_pk_fma_f32 v[4:5], v[4:5], v[144:145], v[162:163]
	v_pk_fma_f32 v[2:3], v[2:3], v[142:143], v[160:161]
	s_nop 0
	global_load_dwordx4 v[148:151], v[164:165], off
	global_load_dwordx4 v[152:155], v[164:165], off offset:64
	global_load_dwordx4 v[156:159], v[164:165], off offset:512
	global_load_dwordx4 v[160:163], v[164:165], off offset:576
	v_add_u32_e32 v164, s18, v224
	v_ashrrev_i32_e32 v165, 31, v164
	v_lshlrev_b64 v[164:165], 14, v[164:165]
	v_lshl_add_u64 v[164:165], v[186:187], 0, v[164:165]
	v_mul_f32_e32 v166, v59, v59
	v_mul_f32_e32 v167, v61, v61
	v_mul_f32_e32 v168, v27, v27
	v_mul_f32_e32 v169, v29, v29
	v_fmac_f32_e32 v166, v58, v58
	v_fmac_f32_e32 v167, v60, v60
	v_mul_f32_e32 v170, v3, v3
	v_mul_f32_e32 v171, v5, v5
	v_fmac_f32_e32 v168, v26, v26
	v_fmac_f32_e32 v169, v28, v28
	v_fmac_f32_e32 v170, v2, v2
	v_fmac_f32_e32 v171, v4, v4
	s_waitcnt vmcnt(7)
	v_pk_fma_f32 v[100:101], v[100:101], v[132:133], v[204:205]
	v_pk_fma_f32 v[98:99], v[98:99], v[130:131], v[202:203]
	s_waitcnt vmcnt(6)
	v_pk_fma_f32 v[68:69], v[68:69], v[140:141], v[208:209]
	v_pk_fma_f32 v[66:67], v[66:67], v[138:139], v[206:207]
	s_waitcnt vmcnt(5)
	v_pk_fma_f32 v[36:37], v[36:37], v[136:137], v[212:213]
	v_pk_fma_f32 v[34:35], v[34:35], v[134:135], v[210:211]
	s_waitcnt vmcnt(4)
	v_pk_fma_f32 v[8:9], v[8:9], v[144:145], v[216:217]
	v_pk_fma_f32 v[6:7], v[6:7], v[142:143], v[214:215]
	s_nop 0
	global_load_dwordx4 v[202:205], v[164:165], off
	global_load_dwordx4 v[206:209], v[164:165], off offset:64
	global_load_dwordx4 v[210:213], v[164:165], off offset:512
	global_load_dwordx4 v[214:217], v[164:165], off offset:576
	v_add_u32_e32 v164, s18, v225
	v_ashrrev_i32_e32 v165, 31, v164
	v_lshlrev_b64 v[164:165], 14, v[164:165]
	v_lshl_add_u64 v[164:165], v[186:187], 0, v[164:165]
	s_waitcnt vmcnt(7)
	v_pk_fma_f32 v[104:105], v[104:105], v[132:133], v[150:151]
	v_pk_fma_f32 v[102:103], v[102:103], v[130:131], v[148:149]
	s_waitcnt vmcnt(6)
	v_pk_fma_f32 v[72:73], v[72:73], v[140:141], v[154:155]
	v_pk_fma_f32 v[70:71], v[70:71], v[138:139], v[152:153]
	s_waitcnt vmcnt(5)
	v_pk_fma_f32 v[40:41], v[40:41], v[136:137], v[158:159]
	v_pk_fma_f32 v[38:39], v[38:39], v[134:135], v[156:157]
	s_waitcnt vmcnt(4)
	v_pk_fma_f32 v[12:13], v[12:13], v[144:145], v[162:163]
	v_pk_fma_f32 v[10:11], v[10:11], v[142:143], v[160:161]
	s_nop 0
	global_load_dwordx4 v[148:151], v[164:165], off
	global_load_dwordx4 v[152:155], v[164:165], off offset:64
	global_load_dwordx4 v[156:159], v[164:165], off offset:512
	global_load_dwordx4 v[160:163], v[164:165], off offset:576
	v_add_u32_e32 v164, 0x90, v146
	v_ashrrev_i32_e32 v165, 31, v164
	v_lshlrev_b64 v[164:165], 14, v[164:165]
	v_lshl_add_u64 v[164:165], v[186:187], 0, v[164:165]
	s_waitcnt vmcnt(7)
	v_pk_fma_f32 v[112:113], v[112:113], v[132:133], v[204:205]
	v_pk_fma_f32 v[110:111], v[110:111], v[130:131], v[202:203]
	s_waitcnt vmcnt(6)
	v_pk_fma_f32 v[80:81], v[80:81], v[140:141], v[208:209]
	v_pk_fma_f32 v[78:79], v[78:79], v[138:139], v[206:207]
	s_waitcnt vmcnt(5)
	v_pk_fma_f32 v[48:49], v[48:49], v[136:137], v[212:213]
	v_pk_fma_f32 v[46:47], v[46:47], v[134:135], v[210:211]
	s_waitcnt vmcnt(4)
	v_pk_fma_f32 v[16:17], v[16:17], v[144:145], v[216:217]
	v_pk_fma_f32 v[14:15], v[14:15], v[142:143], v[214:215]
	s_nop 0
	global_load_dwordx4 v[202:205], v[164:165], off
	global_load_dwordx4 v[206:209], v[164:165], off offset:64
	global_load_dwordx4 v[210:213], v[164:165], off offset:512
	global_load_dwordx4 v[214:217], v[164:165], off offset:576
	v_add_u32_e32 v164, 0xa0, v146
	v_ashrrev_i32_e32 v165, 31, v164
	v_lshlrev_b64 v[164:165], 14, v[164:165]
	v_lshl_add_u64 v[164:165], v[186:187], 0, v[164:165]
	v_add_u32_e32 v146, 0xb0, v146
	v_ashrrev_i32_e32 v147, 31, v146
	v_lshlrev_b64 v[146:147], 14, v[146:147]
	v_lshl_add_u64 v[146:147], v[186:187], 0, v[146:147]
	s_waitcnt vmcnt(7)
	v_pk_fma_f32 v[116:117], v[116:117], v[132:133], v[150:151]
	v_pk_fma_f32 v[114:115], v[114:115], v[130:131], v[148:149]
	s_waitcnt vmcnt(6)
	v_pk_fma_f32 v[84:85], v[84:85], v[140:141], v[154:155]
	v_pk_fma_f32 v[82:83], v[82:83], v[138:139], v[152:153]
	s_waitcnt vmcnt(5)
	v_pk_fma_f32 v[52:53], v[52:53], v[136:137], v[158:159]
	v_pk_fma_f32 v[50:51], v[50:51], v[134:135], v[156:157]
	s_waitcnt vmcnt(4)
	v_pk_fma_f32 v[20:21], v[20:21], v[144:145], v[162:163]
	v_pk_fma_f32 v[18:19], v[18:19], v[142:143], v[160:161]
	s_nop 0
	global_load_dwordx4 v[148:151], v[164:165], off
	global_load_dwordx4 v[152:155], v[164:165], off offset:64
	global_load_dwordx4 v[156:159], v[164:165], off offset:512
	global_load_dwordx4 v[160:163], v[164:165], off offset:576
	s_waitcnt vmcnt(7)
	v_pk_fma_f32 v[120:121], v[120:121], v[132:133], v[204:205]
	v_pk_fma_f32 v[118:119], v[118:119], v[130:131], v[202:203]
	s_waitcnt vmcnt(6)
	v_pk_fma_f32 v[88:89], v[88:89], v[140:141], v[208:209]
	v_pk_fma_f32 v[86:87], v[86:87], v[138:139], v[206:207]
	s_waitcnt vmcnt(5)
	v_pk_fma_f32 v[56:57], v[56:57], v[136:137], v[212:213]
	v_pk_fma_f32 v[54:55], v[54:55], v[134:135], v[210:211]
	s_waitcnt vmcnt(4)
	v_pk_fma_f32 v[24:25], v[24:25], v[144:145], v[216:217]
	v_pk_fma_f32 v[22:23], v[22:23], v[142:143], v[214:215]
	s_nop 0
	global_load_dwordx4 v[202:205], v[146:147], off
	global_load_dwordx4 v[206:209], v[146:147], off offset:64
	global_load_dwordx4 v[210:213], v[146:147], off offset:512
	global_load_dwordx4 v[214:217], v[146:147], off offset:576
	s_waitcnt vmcnt(7)
	v_pk_fma_f32 v[124:125], v[124:125], v[132:133], v[150:151]
	v_pk_fma_f32 v[122:123], v[122:123], v[130:131], v[148:149]
	s_waitcnt vmcnt(6)
	v_pk_fma_f32 v[96:97], v[96:97], v[140:141], v[154:155]
	v_pk_fma_f32 v[94:95], v[94:95], v[138:139], v[152:153]
	s_waitcnt vmcnt(5)
	v_pk_fma_f32 v[64:65], v[64:65], v[136:137], v[158:159]
	v_pk_fma_f32 v[62:63], v[62:63], v[134:135], v[156:157]
	s_waitcnt vmcnt(4)
	v_pk_fma_f32 v[32:33], v[32:33], v[144:145], v[162:163]
	v_pk_fma_f32 v[30:31], v[30:31], v[142:143], v[160:161]
	v_mul_f32_e32 v148, v91, v91
	v_mul_f32_e32 v149, v93, v93
	v_and_b32_e32 v147, 64, v234
	v_fmac_f32_e32 v148, v90, v90
	v_fmac_f32_e32 v149, v92, v92
	v_xor_b32_e32 v146, 16, v234
	v_add_u32_e32 v147, 64, v147
	v_add_f32_e32 v148, v148, v149
	v_add_f32_e32 v149, v166, v167
	v_cmp_lt_i32_e32 vcc, v146, v147
	v_add_f32_e32 v166, v168, v169
	v_add_f32_e32 v148, v148, v149
	v_cndmask_b32_e32 v146, v234, v146, vcc
	v_add_f32_e32 v167, v170, v171
	v_add_f32_e32 v148, v166, v148
	v_lshlrev_b32_e32 v146, 2, v146
	v_add_f32_e32 v148, v167, v148
	ds_bpermute_b32 v149, v146, v148
	v_xor_b32_e32 v166, 32, v234
	v_cmp_lt_i32_e32 vcc, v166, v147
	s_waitcnt vmcnt(3)
	v_pk_fma_f32 v[128:129], v[128:129], v[132:133], v[204:205]
	v_cndmask_b32_e32 v147, v234, v166, vcc
	v_lshlrev_b32_e32 v199, 2, v147
	s_waitcnt lgkmcnt(0)
	v_add_f32_e32 v147, v148, v149
	ds_bpermute_b32 v148, v199, v147
	v_pk_fma_f32 v[126:127], v[126:127], v[130:131], v[202:203]
	s_waitcnt vmcnt(2)
	v_pk_fma_f32 v[108:109], v[108:109], v[140:141], v[208:209]
	v_pk_fma_f32 v[106:107], v[106:107], v[138:139], v[206:207]
	s_waitcnt vmcnt(1)
	v_pk_fma_f32 v[76:77], v[76:77], v[136:137], v[212:213]
	v_pk_fma_f32 v[74:75], v[74:75], v[134:135], v[210:211]
	s_waitcnt vmcnt(0)
	v_pk_fma_f32 v[44:45], v[44:45], v[144:145], v[216:217]
	v_pk_fma_f32 v[42:43], v[42:43], v[142:143], v[214:215]
	s_nop 0
	s_and_saveexec_b64 s[16:17], s[4:5]
	s_cbranch_execz .LBB0_677
	s_waitcnt lgkmcnt(0)
	v_add_f32_e32 v130, v147, v148
	v_add_u32_e32 v131, s80, v226
	ds_write_b32 v131, v130
